# grid-barrier poll loops without s_sleep
# speedup vs baseline: 1.0021x; 1.0021x over previous
.LBB0_3332:
	s_and_b32 s16, s4, 0xff
	s_mov_b64 s[14:15], -1
	s_cmp_lg_u32 s16, 0
	s_mov_b64 s[18:19], -1
	s_cbranch_scc0 .LBB0_3335
	s_and_b64 vcc, exec, s[18:19]
	s_cbranch_vccz .LBB0_3331
